# prologue weight transposes: the 16 LDS read-backs of each item issued together and waited once (were 16 dependent LDS round trips)
# speedup vs baseline: 1.0028x; 1.0028x over previous
.LBB0_703:
	s_or_b64 exec, exec, s[40:41]
	v_add_u32_e32 v0, 0x400, v0
	s_mul_hi_i32 s39, s55, 0x1900000
	s_mul_i32 s55, s55, 0x1900000
	ds_write2_b32 v0, v57, v58 offset0:8 offset1:74
	ds_write2_b32 v0, v59, v60 offset0:140 offset1:206
	s_add_u32 s40, s22, s55
	s_waitcnt lgkmcnt(0)
	s_addc_u32 s41, s23, s39
	s_ashr_i32 s39, s38, 31
	ds_read2_b32 v[112:113], v47 offset1:33
	ds_read2_b32 v[114:115], v47 offset0:66 offset1:99
	ds_read2_b32 v[116:117], v47 offset0:132 offset1:165
	ds_read2_b32 v[118:119], v47 offset0:198 offset1:231
	ds_read2_b32 v[120:121], v47 offset0:8 offset1:41
	ds_read2_b32 v[122:123], v47 offset0:74 offset1:107
	ds_read2_b32 v[124:125], v47 offset0:140 offset1:173
	ds_read2_b32 v[126:127], v47 offset0:206 offset1:239
	ds_read2_b32 v[128:129], v47 offset0:16 offset1:49
	ds_read2_b32 v[130:131], v47 offset0:82 offset1:115
	ds_read2_b32 v[132:133], v47 offset0:148 offset1:181
	ds_read2_b32 v[134:135], v47 offset0:214 offset1:247
	ds_read2_b32 v[136:137], v47 offset0:24 offset1:57
	ds_read2_b32 v[138:139], v47 offset0:90 offset1:123
	ds_read2_b32 v[140:141], v47 offset0:156 offset1:189
	ds_read2_b32 v[142:143], v47 offset0:222 offset1:255
	s_waitcnt lgkmcnt(0)
	s_lshl_b64 s[38:39], s[38:39], 1
	v_cvt_pk_bf16_f32 v58, v112, v113
	v_add_u32_e32 v62, s2, v46
	s_add_u32 s38, s40, s38
	v_lshlrev_b32_e32 v0, 1, v2
	v_cvt_pk_bf16_f32 v59, v114, v115
	v_ashrrev_i32_e32 v63, 31, v62
	s_addc_u32 s39, s41, s39
	v_cvt_pk_bf16_f32 v60, v116, v117
	v_lshlrev_b64 v[62:63], 12, v[62:63]
	v_lshl_add_u64 v[64:65], s[38:39], 0, v[0:1]
	v_cvt_pk_bf16_f32 v61, v118, v119
	v_lshl_add_u64 v[62:63], v[64:65], 0, v[62:63]
	global_store_dwordx4 v[62:63], v[58:61], off
	v_add_u32_e32 v62, s2, v53
	v_ashrrev_i32_e32 v63, 31, v62
	v_cvt_pk_bf16_f32 v58, v120, v121
	v_cvt_pk_bf16_f32 v59, v122, v123
	v_cvt_pk_bf16_f32 v60, v124, v125
	v_lshlrev_b64 v[62:63], 12, v[62:63]
	v_cvt_pk_bf16_f32 v61, v126, v127
	v_lshl_add_u64 v[62:63], v[64:65], 0, v[62:63]
	global_store_dwordx4 v[62:63], v[58:61], off
	v_add_u32_e32 v62, s2, v54
	v_ashrrev_i32_e32 v63, 31, v62
	v_cvt_pk_bf16_f32 v58, v128, v129
	v_cvt_pk_bf16_f32 v59, v130, v131
	v_cvt_pk_bf16_f32 v60, v132, v133
	v_lshlrev_b64 v[62:63], 12, v[62:63]
	v_cvt_pk_bf16_f32 v61, v134, v135
	v_lshl_add_u64 v[62:63], v[64:65], 0, v[62:63]
	global_store_dwordx4 v[62:63], v[58:61], off
	v_add_u32_e32 v62, s2, v55
	v_ashrrev_i32_e32 v63, 31, v62
	v_cvt_pk_bf16_f32 v58, v136, v137
	v_cvt_pk_bf16_f32 v59, v138, v139
	v_cvt_pk_bf16_f32 v60, v140, v141
	v_lshlrev_b64 v[62:63], 12, v[62:63]
	v_cvt_pk_bf16_f32 v61, v142, v143
	v_lshl_add_u64 v[6:7], v[64:65], 0, v[62:63]
	global_store_dwordx4 v[6:7], v[58:61], off
	s_waitcnt lgkmcnt(0)

.LBB0_707:
	s_cmpk_gt_u32 s17, 0x41ff
	s_cbranch_scc0 .LBB0_725
	s_cmpk_gt_u32 s17, 0x61ff
	s_cbranch_scc0 .LBB0_722
	s_cmpk_gt_u32 s17, 0x71ff
	s_cbranch_scc0 .LBB0_719
	s_cmpk_gt_u32 s17, 0x81ff
	s_cbranch_scc0 .LBB0_716
	s_cmpk_gt_u32 s17, 0x85ff
	s_cbranch_scc0 .LBB0_713
	s_add_i32 s40, s17, 0xffff7a00
	s_and_b32 s2, s40, 0xfffff800
	s_lshl_b64 s[38:39], s[2:3], 13
	s_add_u32 s42, s6, s38
	s_addc_u32 s43, s7, s39
	s_lshl_b64 s[38:39], s[2:3], 12
	s_add_u32 s38, s33, s38
	s_addc_u32 s39, s44, s39
	s_and_b32 s40, s40, 0x7c0
	s_and_b32 s2, s53, 0x7e0
	v_or_b32_e32 v0, s2, v3
	v_add_u32_e32 v58, s40, v8
	v_add_u32_e32 v60, s40, v11
	v_add_u32_e32 v62, s40, v12
	v_add_u32_e32 v64, s40, v13
	v_add_u32_e32 v66, s40, v14
	v_add_u32_e32 v68, s40, v15
	v_add_u32_e32 v70, s40, v16
	v_add_u32_e32 v72, s40, v18
	v_lshlrev_b32_e32 v0, 2, v0
	v_ashrrev_i32_e32 v59, 31, v58
	v_ashrrev_i32_e32 v61, 31, v60
	v_ashrrev_i32_e32 v63, 31, v62
	v_ashrrev_i32_e32 v65, 31, v64
	v_ashrrev_i32_e32 v67, 31, v66
	v_ashrrev_i32_e32 v69, 31, v68
	v_ashrrev_i32_e32 v71, 31, v70
	v_ashrrev_i32_e32 v73, 31, v72
	v_lshl_add_u64 v[6:7], s[42:43], 0, v[0:1]
	v_lshlrev_b64 v[58:59], 13, v[58:59]
	v_lshlrev_b64 v[60:61], 13, v[60:61]
	v_lshlrev_b64 v[62:63], 13, v[62:63]
	v_lshlrev_b64 v[64:65], 13, v[64:65]
	v_lshlrev_b64 v[66:67], 13, v[66:67]
	v_lshlrev_b64 v[68:69], 13, v[68:69]
	v_lshlrev_b64 v[70:71], 13, v[70:71]
	v_lshlrev_b64 v[72:73], 13, v[72:73]
	v_lshl_add_u64 v[58:59], v[6:7], 0, v[58:59]
	v_lshl_add_u64 v[60:61], v[6:7], 0, v[60:61]
	v_lshl_add_u64 v[62:63], v[6:7], 0, v[62:63]
	v_lshl_add_u64 v[64:65], v[6:7], 0, v[64:65]
	v_lshl_add_u64 v[66:67], v[6:7], 0, v[66:67]
	v_lshl_add_u64 v[68:69], v[6:7], 0, v[68:69]
	v_lshl_add_u64 v[70:71], v[6:7], 0, v[70:71]
	v_lshl_add_u64 v[72:73], v[6:7], 0, v[72:73]
	global_load_dword v0, v[58:59], off
	global_load_dword v57, v[60:61], off
	global_load_dword v74, v[62:63], off
	global_load_dword v75, v[64:65], off
	global_load_dword v76, v[66:67], off
	global_load_dword v77, v[68:69], off
	global_load_dword v78, v[70:71], off
	global_load_dword v79, v[72:73], off
	v_add_u32_e32 v58, s40, v19
	v_add_u32_e32 v60, s40, v20
	v_add_u32_e32 v62, s40, v21
	v_add_u32_e32 v64, s40, v22
	v_add_u32_e32 v66, s40, v23
	v_add_u32_e32 v68, s40, v25
	v_add_u32_e32 v70, s40, v26
	v_add_u32_e32 v72, s40, v27
	v_ashrrev_i32_e32 v59, 31, v58
	v_ashrrev_i32_e32 v61, 31, v60
	v_ashrrev_i32_e32 v63, 31, v62
	v_ashrrev_i32_e32 v65, 31, v64
	v_ashrrev_i32_e32 v67, 31, v66
	v_ashrrev_i32_e32 v69, 31, v68
	v_ashrrev_i32_e32 v71, 31, v70
	v_ashrrev_i32_e32 v73, 31, v72
	v_lshlrev_b64 v[58:59], 13, v[58:59]
	v_lshlrev_b64 v[60:61], 13, v[60:61]
	v_lshlrev_b64 v[62:63], 13, v[62:63]
	v_lshlrev_b64 v[64:65], 13, v[64:65]
	v_lshlrev_b64 v[66:67], 13, v[66:67]
	v_lshlrev_b64 v[68:69], 13, v[68:69]
	v_lshlrev_b64 v[70:71], 13, v[70:71]
	v_lshlrev_b64 v[72:73], 13, v[72:73]
	v_lshl_add_u64 v[58:59], v[6:7], 0, v[58:59]
	v_lshl_add_u64 v[60:61], v[6:7], 0, v[60:61]
	v_lshl_add_u64 v[62:63], v[6:7], 0, v[62:63]
	v_lshl_add_u64 v[64:65], v[6:7], 0, v[64:65]
	v_lshl_add_u64 v[66:67], v[6:7], 0, v[66:67]
	v_lshl_add_u64 v[68:69], v[6:7], 0, v[68:69]
	v_lshl_add_u64 v[70:71], v[6:7], 0, v[70:71]
	v_lshl_add_u64 v[72:73], v[6:7], 0, v[72:73]
	global_load_dword v80, v[58:59], off
	global_load_dword v81, v[60:61], off
	global_load_dword v82, v[62:63], off
	global_load_dword v83, v[64:65], off
	global_load_dword v84, v[66:67], off
	global_load_dword v85, v[68:69], off
	global_load_dword v86, v[70:71], off
	global_load_dword v87, v[72:73], off
	v_add_u32_e32 v58, s40, v28
	v_add_u32_e32 v60, s40, v29
	v_add_u32_e32 v62, s40, v30
	v_add_u32_e32 v64, s40, v32
	v_add_u32_e32 v66, s40, v33
	v_add_u32_e32 v68, s40, v34
	v_add_u32_e32 v70, s40, v35
	v_add_u32_e32 v72, s40, v36
	v_ashrrev_i32_e32 v59, 31, v58
	v_ashrrev_i32_e32 v61, 31, v60
	v_ashrrev_i32_e32 v63, 31, v62
	v_ashrrev_i32_e32 v65, 31, v64
	v_ashrrev_i32_e32 v67, 31, v66
	v_ashrrev_i32_e32 v69, 31, v68
	v_ashrrev_i32_e32 v71, 31, v70
	v_ashrrev_i32_e32 v73, 31, v72
	v_lshlrev_b64 v[58:59], 13, v[58:59]
	v_lshlrev_b64 v[60:61], 13, v[60:61]
	v_lshlrev_b64 v[62:63], 13, v[62:63]
	v_lshlrev_b64 v[64:65], 13, v[64:65]
	v_lshlrev_b64 v[66:67], 13, v[66:67]
	v_lshlrev_b64 v[68:69], 13, v[68:69]
	v_lshlrev_b64 v[70:71], 13, v[70:71]
	v_lshlrev_b64 v[72:73], 13, v[72:73]
	v_lshl_add_u64 v[58:59], v[6:7], 0, v[58:59]
	v_lshl_add_u64 v[60:61], v[6:7], 0, v[60:61]
	v_lshl_add_u64 v[62:63], v[6:7], 0, v[62:63]
	v_lshl_add_u64 v[64:65], v[6:7], 0, v[64:65]
	v_lshl_add_u64 v[66:67], v[6:7], 0, v[66:67]
	v_lshl_add_u64 v[68:69], v[6:7], 0, v[68:69]
	v_lshl_add_u64 v[70:71], v[6:7], 0, v[70:71]
	v_lshl_add_u64 v[72:73], v[6:7], 0, v[72:73]
	global_load_dword v88, v[58:59], off
	global_load_dword v89, v[60:61], off
	global_load_dword v90, v[62:63], off
	global_load_dword v91, v[64:65], off
	global_load_dword v92, v[66:67], off
	global_load_dword v93, v[68:69], off
	global_load_dword v94, v[70:71], off
	global_load_dword v95, v[72:73], off
	v_add_u32_e32 v58, s40, v37
	v_add_u32_e32 v60, s40, v39
	v_add_u32_e32 v62, s40, v40
	v_add_u32_e32 v64, s40, v41
	v_add_u32_e32 v66, s40, v42
	v_add_u32_e32 v68, s40, v43
	v_add_u32_e32 v70, s40, v44
	v_add_u32_e32 v72, s40, v45
	v_ashrrev_i32_e32 v59, 31, v58
	v_ashrrev_i32_e32 v61, 31, v60
	v_ashrrev_i32_e32 v63, 31, v62
	v_ashrrev_i32_e32 v65, 31, v64
	v_ashrrev_i32_e32 v67, 31, v66
	v_ashrrev_i32_e32 v69, 31, v68
	v_ashrrev_i32_e32 v71, 31, v70
	v_ashrrev_i32_e32 v73, 31, v72
	v_lshlrev_b64 v[58:59], 13, v[58:59]
	v_lshlrev_b64 v[60:61], 13, v[60:61]
	v_lshlrev_b64 v[62:63], 13, v[62:63]
	v_lshlrev_b64 v[64:65], 13, v[64:65]
	v_lshlrev_b64 v[66:67], 13, v[66:67]
	v_lshlrev_b64 v[68:69], 13, v[68:69]
	v_lshlrev_b64 v[70:71], 13, v[70:71]
	v_lshlrev_b64 v[72:73], 13, v[72:73]
	v_lshl_add_u64 v[58:59], v[6:7], 0, v[58:59]
	v_lshl_add_u64 v[60:61], v[6:7], 0, v[60:61]
	v_lshl_add_u64 v[62:63], v[6:7], 0, v[62:63]
	v_lshl_add_u64 v[64:65], v[6:7], 0, v[64:65]
	v_lshl_add_u64 v[66:67], v[6:7], 0, v[66:67]
	v_lshl_add_u64 v[68:69], v[6:7], 0, v[68:69]
	v_lshl_add_u64 v[70:71], v[6:7], 0, v[70:71]
	v_lshl_add_u64 v[6:7], v[6:7], 0, v[72:73]
	global_load_dword v58, v[58:59], off
	s_nop 0
	global_load_dword v59, v[60:61], off
	s_nop 0
	global_load_dword v60, v[62:63], off
	global_load_dword v61, v[64:65], off
	s_nop 0
	global_load_dword v62, v[66:67], off
	global_load_dword v63, v[68:69], off
	global_load_dword v64, v[70:71], off
	s_nop 0
	global_load_dword v6, v[6:7], off
	v_add_u32_e32 v7, v9, v10
	s_waitcnt vmcnt(0)
	ds_write2_b32 v7, v0, v57 offset1:66
	ds_write2_b32 v7, v74, v75 offset0:132 offset1:198
	v_add_u32_e32 v0, 0x400, v7
	ds_write2_b32 v0, v76, v77 offset0:8 offset1:74
	v_add_u32_e32 v0, v9, v17
	ds_write2_b32 v0, v78, v79 offset1:66
	ds_write2_b32 v0, v80, v81 offset0:132 offset1:198
	v_add_u32_e32 v0, 0x400, v0
	ds_write2_b32 v0, v82, v83 offset0:8 offset1:74
	v_add_u32_e32 v0, v9, v24
	ds_write2_b32 v0, v84, v85 offset1:66
	ds_write2_b32 v0, v86, v87 offset0:132 offset1:198
	v_add_u32_e32 v0, 0x400, v0
	s_lshl_b32 s40, s40, 1
	s_add_u32 s38, s38, s40
	s_addc_u32 s39, s39, 0
	ds_write2_b32 v0, v88, v89 offset0:8 offset1:74
	v_add_u32_e32 v0, v9, v31
	ds_write2_b32 v0, v90, v91 offset1:66
	ds_write2_b32 v0, v92, v93 offset0:132 offset1:198
	v_add_u32_e32 v0, 0x400, v0
	ds_write2_b32 v0, v94, v95 offset0:8 offset1:74
	v_add_u32_e32 v0, v9, v38
	ds_write2_b32 v0, v58, v59 offset1:66
	ds_write2_b32 v0, v60, v61 offset0:132 offset1:198
	v_add_u32_e32 v0, 0x400, v0
	ds_write2_b32 v0, v62, v63 offset0:8 offset1:74
	ds_write2_b32 v0, v64, v6 offset0:140 offset1:206
	s_waitcnt lgkmcnt(0)
	ds_read2_b32 v[112:113], v47 offset1:33
	ds_read2_b32 v[114:115], v47 offset0:66 offset1:99
	ds_read2_b32 v[116:117], v47 offset0:132 offset1:165
	ds_read2_b32 v[118:119], v47 offset0:198 offset1:231
	ds_read2_b32 v[120:121], v47 offset0:8 offset1:41
	ds_read2_b32 v[122:123], v47 offset0:74 offset1:107
	ds_read2_b32 v[124:125], v47 offset0:140 offset1:173
	ds_read2_b32 v[126:127], v47 offset0:206 offset1:239
	ds_read2_b32 v[128:129], v47 offset0:16 offset1:49
	ds_read2_b32 v[130:131], v47 offset0:82 offset1:115
	ds_read2_b32 v[132:133], v47 offset0:148 offset1:181
	ds_read2_b32 v[134:135], v47 offset0:214 offset1:247
	ds_read2_b32 v[136:137], v47 offset0:24 offset1:57
	ds_read2_b32 v[138:139], v47 offset0:90 offset1:123
	ds_read2_b32 v[140:141], v47 offset0:156 offset1:189
	ds_read2_b32 v[142:143], v47 offset0:222 offset1:255
	s_waitcnt lgkmcnt(0)
	v_cvt_pk_bf16_f32 v58, v112, v113
	v_cvt_pk_bf16_f32 v59, v114, v115
	v_cvt_pk_bf16_f32 v60, v116, v117
	v_cvt_pk_bf16_f32 v61, v118, v119
	v_add_u32_e32 v6, s2, v46
	v_lshlrev_b32_e32 v0, 1, v2
	v_ashrrev_i32_e32 v7, 31, v6
	v_lshl_add_u64 v[62:63], s[38:39], 0, v[0:1]
	v_lshlrev_b64 v[6:7], 12, v[6:7]
	v_lshl_add_u64 v[6:7], v[62:63], 0, v[6:7]
	global_store_dwordx4 v[6:7], v[58:61], off
	s_mov_b64 s[38:39], 0
	v_cvt_pk_bf16_f32 v58, v120, v121
	v_cvt_pk_bf16_f32 v59, v122, v123
	v_cvt_pk_bf16_f32 v60, v124, v125
	v_cvt_pk_bf16_f32 v61, v126, v127
	v_add_u32_e32 v6, s2, v53
	v_ashrrev_i32_e32 v7, 31, v6
	v_lshlrev_b64 v[6:7], 12, v[6:7]
	v_lshl_add_u64 v[6:7], v[62:63], 0, v[6:7]
	global_store_dwordx4 v[6:7], v[58:61], off
	s_nop 0
	v_cvt_pk_bf16_f32 v58, v128, v129
	v_cvt_pk_bf16_f32 v59, v130, v131
	v_cvt_pk_bf16_f32 v60, v132, v133
	v_cvt_pk_bf16_f32 v61, v134, v135
	v_add_u32_e32 v6, s2, v54
	v_ashrrev_i32_e32 v7, 31, v6
	v_lshlrev_b64 v[6:7], 12, v[6:7]
	v_lshl_add_u64 v[6:7], v[62:63], 0, v[6:7]
	global_store_dwordx4 v[6:7], v[58:61], off
	s_nop 0
	v_cvt_pk_bf16_f32 v58, v136, v137
	v_cvt_pk_bf16_f32 v59, v138, v139
	v_cvt_pk_bf16_f32 v60, v140, v141
	v_cvt_pk_bf16_f32 v61, v142, v143
	v_add_u32_e32 v6, s2, v55
	v_ashrrev_i32_e32 v7, 31, v6
	v_lshlrev_b64 v[6:7], 12, v[6:7]
	v_lshl_add_u64 v[6:7], v[62:63], 0, v[6:7]
	global_store_dwordx4 v[6:7], v[58:61], off
	s_waitcnt lgkmcnt(0)
.LBB0_713:
	s_andn2_b64 vcc, exec, s[38:39]
	s_cbranch_vccnz .LBB0_715
	s_add_i32 s2, s17, 0xffff7e00
	s_lshr_b32 s2, s2, 8
	s_lshl_b64 s[38:39], s[2:3], 21
	s_add_u32 s42, s34, s38
	s_addc_u32 s43, s35, s39
	s_lshl_b64 s[38:39], s[2:3], 20
	s_add_u32 s38, s45, s38
	s_addc_u32 s39, s46, s39
	s_and_b32 s40, s17, 0xc0
	s_and_b32 s2, s53, 0x7e0
	v_or_b32_e32 v0, s2, v3
	v_add_u32_e32 v58, s40, v8
	v_add_u32_e32 v60, s40, v11
	v_add_u32_e32 v62, s40, v12
	v_add_u32_e32 v64, s40, v13
	v_add_u32_e32 v66, s40, v14
	v_add_u32_e32 v68, s40, v15
	v_add_u32_e32 v70, s40, v16
	v_add_u32_e32 v72, s40, v18
	v_lshlrev_b32_e32 v0, 2, v0
	v_ashrrev_i32_e32 v59, 31, v58
	v_ashrrev_i32_e32 v61, 31, v60
	v_ashrrev_i32_e32 v63, 31, v62
	v_ashrrev_i32_e32 v65, 31, v64
	v_ashrrev_i32_e32 v67, 31, v66
	v_ashrrev_i32_e32 v69, 31, v68
	v_ashrrev_i32_e32 v71, 31, v70
	v_ashrrev_i32_e32 v73, 31, v72
	v_lshl_add_u64 v[6:7], s[42:43], 0, v[0:1]
	v_lshlrev_b64 v[58:59], 13, v[58:59]
	v_lshlrev_b64 v[60:61], 13, v[60:61]
	v_lshlrev_b64 v[62:63], 13, v[62:63]
	v_lshlrev_b64 v[64:65], 13, v[64:65]
	v_lshlrev_b64 v[66:67], 13, v[66:67]
	v_lshlrev_b64 v[68:69], 13, v[68:69]
	v_lshlrev_b64 v[70:71], 13, v[70:71]
	v_lshlrev_b64 v[72:73], 13, v[72:73]
	v_lshl_add_u64 v[58:59], v[6:7], 0, v[58:59]
	v_lshl_add_u64 v[60:61], v[6:7], 0, v[60:61]
	v_lshl_add_u64 v[62:63], v[6:7], 0, v[62:63]
	v_lshl_add_u64 v[64:65], v[6:7], 0, v[64:65]
	v_lshl_add_u64 v[66:67], v[6:7], 0, v[66:67]
	v_lshl_add_u64 v[68:69], v[6:7], 0, v[68:69]
	v_lshl_add_u64 v[70:71], v[6:7], 0, v[70:71]
	v_lshl_add_u64 v[72:73], v[6:7], 0, v[72:73]
	global_load_dword v0, v[58:59], off
	global_load_dword v57, v[60:61], off
	global_load_dword v74, v[62:63], off
	global_load_dword v75, v[64:65], off
	global_load_dword v76, v[66:67], off
	global_load_dword v77, v[68:69], off
	global_load_dword v78, v[70:71], off
	global_load_dword v79, v[72:73], off
	v_add_u32_e32 v58, s40, v19
	v_add_u32_e32 v60, s40, v20
	v_add_u32_e32 v62, s40, v21
	v_add_u32_e32 v64, s40, v22
	v_add_u32_e32 v66, s40, v23
	v_add_u32_e32 v68, s40, v25
	v_add_u32_e32 v70, s40, v26
	v_add_u32_e32 v72, s40, v27
	v_ashrrev_i32_e32 v59, 31, v58
	v_ashrrev_i32_e32 v61, 31, v60
	v_ashrrev_i32_e32 v63, 31, v62
	v_ashrrev_i32_e32 v65, 31, v64
	v_ashrrev_i32_e32 v67, 31, v66
	v_ashrrev_i32_e32 v69, 31, v68
	v_ashrrev_i32_e32 v71, 31, v70
	v_ashrrev_i32_e32 v73, 31, v72
	v_lshlrev_b64 v[58:59], 13, v[58:59]
	v_lshlrev_b64 v[60:61], 13, v[60:61]
	v_lshlrev_b64 v[62:63], 13, v[62:63]
	v_lshlrev_b64 v[64:65], 13, v[64:65]
	v_lshlrev_b64 v[66:67], 13, v[66:67]
	v_lshlrev_b64 v[68:69], 13, v[68:69]
	v_lshlrev_b64 v[70:71], 13, v[70:71]
	v_lshlrev_b64 v[72:73], 13, v[72:73]
	v_lshl_add_u64 v[58:59], v[6:7], 0, v[58:59]
	v_lshl_add_u64 v[60:61], v[6:7], 0, v[60:61]
	v_lshl_add_u64 v[62:63], v[6:7], 0, v[62:63]
	v_lshl_add_u64 v[64:65], v[6:7], 0, v[64:65]
	v_lshl_add_u64 v[66:67], v[6:7], 0, v[66:67]
	v_lshl_add_u64 v[68:69], v[6:7], 0, v[68:69]
	v_lshl_add_u64 v[70:71], v[6:7], 0, v[70:71]
	v_lshl_add_u64 v[72:73], v[6:7], 0, v[72:73]
	global_load_dword v80, v[58:59], off
	global_load_dword v81, v[60:61], off
	global_load_dword v82, v[62:63], off
	global_load_dword v83, v[64:65], off
	global_load_dword v84, v[66:67], off
	global_load_dword v85, v[68:69], off
	global_load_dword v86, v[70:71], off
	global_load_dword v87, v[72:73], off
	v_add_u32_e32 v58, s40, v28
	v_add_u32_e32 v60, s40, v29
	v_add_u32_e32 v62, s40, v30
	v_add_u32_e32 v64, s40, v32
	v_add_u32_e32 v66, s40, v33
	v_add_u32_e32 v68, s40, v34
	v_add_u32_e32 v70, s40, v35
	v_add_u32_e32 v72, s40, v36
	v_ashrrev_i32_e32 v59, 31, v58
	v_ashrrev_i32_e32 v61, 31, v60
	v_ashrrev_i32_e32 v63, 31, v62
	v_ashrrev_i32_e32 v65, 31, v64
	v_ashrrev_i32_e32 v67, 31, v66
	v_ashrrev_i32_e32 v69, 31, v68
	v_ashrrev_i32_e32 v71, 31, v70
	v_ashrrev_i32_e32 v73, 31, v72
	v_lshlrev_b64 v[58:59], 13, v[58:59]
	v_lshlrev_b64 v[60:61], 13, v[60:61]
	v_lshlrev_b64 v[62:63], 13, v[62:63]
	v_lshlrev_b64 v[64:65], 13, v[64:65]
	v_lshlrev_b64 v[66:67], 13, v[66:67]
	v_lshlrev_b64 v[68:69], 13, v[68:69]
	v_lshlrev_b64 v[70:71], 13, v[70:71]
	v_lshlrev_b64 v[72:73], 13, v[72:73]
	v_lshl_add_u64 v[58:59], v[6:7], 0, v[58:59]
	v_lshl_add_u64 v[60:61], v[6:7], 0, v[60:61]
	v_lshl_add_u64 v[62:63], v[6:7], 0, v[62:63]
	v_lshl_add_u64 v[64:65], v[6:7], 0, v[64:65]
	v_lshl_add_u64 v[66:67], v[6:7], 0, v[66:67]
	v_lshl_add_u64 v[68:69], v[6:7], 0, v[68:69]
	v_lshl_add_u64 v[70:71], v[6:7], 0, v[70:71]
	v_lshl_add_u64 v[72:73], v[6:7], 0, v[72:73]
	global_load_dword v88, v[58:59], off
	global_load_dword v89, v[60:61], off
	global_load_dword v90, v[62:63], off
	global_load_dword v91, v[64:65], off
	global_load_dword v92, v[66:67], off
	global_load_dword v93, v[68:69], off
	global_load_dword v94, v[70:71], off
	global_load_dword v95, v[72:73], off
	v_add_u32_e32 v58, s40, v37
	v_add_u32_e32 v60, s40, v39
	v_add_u32_e32 v62, s40, v40
	v_add_u32_e32 v64, s40, v41
	v_add_u32_e32 v66, s40, v42
	v_add_u32_e32 v68, s40, v43
	v_add_u32_e32 v70, s40, v44
	v_add_u32_e32 v72, s40, v45
	v_ashrrev_i32_e32 v59, 31, v58
	v_ashrrev_i32_e32 v61, 31, v60
	v_ashrrev_i32_e32 v63, 31, v62
	v_ashrrev_i32_e32 v65, 31, v64
	v_ashrrev_i32_e32 v67, 31, v66
	v_ashrrev_i32_e32 v69, 31, v68
	v_ashrrev_i32_e32 v71, 31, v70
	v_ashrrev_i32_e32 v73, 31, v72
	v_lshlrev_b64 v[58:59], 13, v[58:59]
	v_lshlrev_b64 v[60:61], 13, v[60:61]
	v_lshlrev_b64 v[62:63], 13, v[62:63]
	v_lshlrev_b64 v[64:65], 13, v[64:65]
	v_lshlrev_b64 v[66:67], 13, v[66:67]
	v_lshlrev_b64 v[68:69], 13, v[68:69]
	v_lshlrev_b64 v[70:71], 13, v[70:71]
	v_lshlrev_b64 v[72:73], 13, v[72:73]
	v_lshl_add_u64 v[58:59], v[6:7], 0, v[58:59]
	v_lshl_add_u64 v[60:61], v[6:7], 0, v[60:61]
	v_lshl_add_u64 v[62:63], v[6:7], 0, v[62:63]
	v_lshl_add_u64 v[64:65], v[6:7], 0, v[64:65]
	v_lshl_add_u64 v[66:67], v[6:7], 0, v[66:67]
	v_lshl_add_u64 v[68:69], v[6:7], 0, v[68:69]
	v_lshl_add_u64 v[70:71], v[6:7], 0, v[70:71]
	v_lshl_add_u64 v[6:7], v[6:7], 0, v[72:73]
	global_load_dword v58, v[58:59], off
	s_nop 0
	global_load_dword v59, v[60:61], off
	s_nop 0
	global_load_dword v60, v[62:63], off
	global_load_dword v61, v[64:65], off
	s_nop 0
	global_load_dword v62, v[66:67], off
	global_load_dword v63, v[68:69], off
	global_load_dword v64, v[70:71], off
	s_nop 0
	global_load_dword v6, v[6:7], off
	v_add_u32_e32 v7, v9, v10
	s_waitcnt vmcnt(0)
	ds_write2_b32 v7, v0, v57 offset1:66
	ds_write2_b32 v7, v74, v75 offset0:132 offset1:198
	v_add_u32_e32 v0, 0x400, v7
	ds_write2_b32 v0, v76, v77 offset0:8 offset1:74
	v_add_u32_e32 v0, v9, v17
	ds_write2_b32 v0, v78, v79 offset1:66
	ds_write2_b32 v0, v80, v81 offset0:132 offset1:198
	v_add_u32_e32 v0, 0x400, v0
	ds_write2_b32 v0, v82, v83 offset0:8 offset1:74
	v_add_u32_e32 v0, v9, v24
	ds_write2_b32 v0, v84, v85 offset1:66
	ds_write2_b32 v0, v86, v87 offset0:132 offset1:198
	v_add_u32_e32 v0, 0x400, v0
	s_lshl_b32 s40, s40, 1
	s_add_u32 s38, s38, s40
	s_addc_u32 s39, s39, 0
	ds_write2_b32 v0, v88, v89 offset0:8 offset1:74
	v_add_u32_e32 v0, v9, v31
	ds_write2_b32 v0, v90, v91 offset1:66
	ds_write2_b32 v0, v92, v93 offset0:132 offset1:198
	v_add_u32_e32 v0, 0x400, v0
	ds_write2_b32 v0, v94, v95 offset0:8 offset1:74
	v_add_u32_e32 v0, v9, v38
	ds_write2_b32 v0, v58, v59 offset1:66
	ds_write2_b32 v0, v60, v61 offset0:132 offset1:198
	v_add_u32_e32 v0, 0x400, v0
	ds_write2_b32 v0, v62, v63 offset0:8 offset1:74
	ds_write2_b32 v0, v64, v6 offset0:140 offset1:206
	s_waitcnt lgkmcnt(0)
	ds_read2_b32 v[112:113], v47 offset1:33
	ds_read2_b32 v[114:115], v47 offset0:66 offset1:99
	ds_read2_b32 v[116:117], v47 offset0:132 offset1:165
	ds_read2_b32 v[118:119], v47 offset0:198 offset1:231
	ds_read2_b32 v[120:121], v47 offset0:8 offset1:41
	ds_read2_b32 v[122:123], v47 offset0:74 offset1:107
	ds_read2_b32 v[124:125], v47 offset0:140 offset1:173
	ds_read2_b32 v[126:127], v47 offset0:206 offset1:239
	ds_read2_b32 v[128:129], v47 offset0:16 offset1:49
	ds_read2_b32 v[130:131], v47 offset0:82 offset1:115
	ds_read2_b32 v[132:133], v47 offset0:148 offset1:181
	ds_read2_b32 v[134:135], v47 offset0:214 offset1:247
	ds_read2_b32 v[136:137], v47 offset0:24 offset1:57
	ds_read2_b32 v[138:139], v47 offset0:90 offset1:123
	ds_read2_b32 v[140:141], v47 offset0:156 offset1:189
	ds_read2_b32 v[142:143], v47 offset0:222 offset1:255
	s_waitcnt lgkmcnt(0)
	v_cvt_pk_bf16_f32 v58, v112, v113
	v_cvt_pk_bf16_f32 v59, v114, v115
	v_cvt_pk_bf16_f32 v60, v116, v117
	v_cvt_pk_bf16_f32 v61, v118, v119
	v_add_u32_e32 v6, s2, v46
	v_lshlrev_b32_e32 v0, 1, v2
	v_ashrrev_i32_e32 v7, 31, v6
	v_lshl_add_u64 v[62:63], s[38:39], 0, v[0:1]
	v_lshlrev_b64 v[6:7], 9, v[6:7]
	v_lshl_add_u64 v[6:7], v[62:63], 0, v[6:7]
	global_store_dwordx4 v[6:7], v[58:61], off
	s_nop 0
	v_cvt_pk_bf16_f32 v58, v120, v121
	v_cvt_pk_bf16_f32 v59, v122, v123
	v_cvt_pk_bf16_f32 v60, v124, v125
	v_cvt_pk_bf16_f32 v61, v126, v127
	v_add_u32_e32 v6, s2, v53
	v_ashrrev_i32_e32 v7, 31, v6
	v_lshlrev_b64 v[6:7], 9, v[6:7]
	v_lshl_add_u64 v[6:7], v[62:63], 0, v[6:7]
	global_store_dwordx4 v[6:7], v[58:61], off
	s_nop 0
	v_cvt_pk_bf16_f32 v58, v128, v129
	v_cvt_pk_bf16_f32 v59, v130, v131
	v_cvt_pk_bf16_f32 v60, v132, v133
	v_cvt_pk_bf16_f32 v61, v134, v135
	v_add_u32_e32 v6, s2, v54
	v_ashrrev_i32_e32 v7, 31, v6
	v_lshlrev_b64 v[6:7], 9, v[6:7]
	v_lshl_add_u64 v[6:7], v[62:63], 0, v[6:7]
	global_store_dwordx4 v[6:7], v[58:61], off
	s_nop 0
	v_cvt_pk_bf16_f32 v58, v136, v137
	v_cvt_pk_bf16_f32 v59, v138, v139
	v_cvt_pk_bf16_f32 v60, v140, v141
	v_cvt_pk_bf16_f32 v61, v142, v143
	v_add_u32_e32 v6, s2, v55
	v_ashrrev_i32_e32 v7, 31, v6
	v_lshlrev_b64 v[6:7], 9, v[6:7]
	v_lshl_add_u64 v[6:7], v[62:63], 0, v[6:7]
	global_store_dwordx4 v[6:7], v[58:61], off
	s_waitcnt lgkmcnt(0)

.LBB0_716:
	s_andn2_b64 vcc, exec, s[38:39]
	s_cbranch_vccnz .LBB0_718
	s_add_i32 s40, s17, 0xffff8e00
	s_and_b32 s2, s40, 0xfffff800
	s_lshl_b64 s[38:39], s[2:3], 13
	s_add_u32 s42, s36, s38
	s_addc_u32 s43, s37, s39
	s_lshl_b64 s[38:39], s[2:3], 12
	s_add_u32 s38, s47, s38
	s_addc_u32 s39, s48, s39
	s_and_b32 s40, s40, 0x7c0
	s_and_b32 s2, s53, 0x7e0
	v_or_b32_e32 v0, s2, v3
	v_add_u32_e32 v58, s40, v8
	v_add_u32_e32 v60, s40, v11
	v_add_u32_e32 v62, s40, v12
	v_add_u32_e32 v64, s40, v13
	v_add_u32_e32 v66, s40, v14
	v_add_u32_e32 v68, s40, v15
	v_add_u32_e32 v70, s40, v16
	v_add_u32_e32 v72, s40, v18
	v_lshlrev_b32_e32 v0, 2, v0
	v_ashrrev_i32_e32 v59, 31, v58
	v_ashrrev_i32_e32 v61, 31, v60
	v_ashrrev_i32_e32 v63, 31, v62
	v_ashrrev_i32_e32 v65, 31, v64
	v_ashrrev_i32_e32 v67, 31, v66
	v_ashrrev_i32_e32 v69, 31, v68
	v_ashrrev_i32_e32 v71, 31, v70
	v_ashrrev_i32_e32 v73, 31, v72
	v_lshl_add_u64 v[6:7], s[42:43], 0, v[0:1]
	v_lshlrev_b64 v[58:59], 13, v[58:59]
	v_lshlrev_b64 v[60:61], 13, v[60:61]
	v_lshlrev_b64 v[62:63], 13, v[62:63]
	v_lshlrev_b64 v[64:65], 13, v[64:65]
	v_lshlrev_b64 v[66:67], 13, v[66:67]
	v_lshlrev_b64 v[68:69], 13, v[68:69]
	v_lshlrev_b64 v[70:71], 13, v[70:71]
	v_lshlrev_b64 v[72:73], 13, v[72:73]
	v_lshl_add_u64 v[58:59], v[6:7], 0, v[58:59]
	v_lshl_add_u64 v[60:61], v[6:7], 0, v[60:61]
	v_lshl_add_u64 v[62:63], v[6:7], 0, v[62:63]
	v_lshl_add_u64 v[64:65], v[6:7], 0, v[64:65]
	v_lshl_add_u64 v[66:67], v[6:7], 0, v[66:67]
	v_lshl_add_u64 v[68:69], v[6:7], 0, v[68:69]
	v_lshl_add_u64 v[70:71], v[6:7], 0, v[70:71]
	v_lshl_add_u64 v[72:73], v[6:7], 0, v[72:73]
	global_load_dword v0, v[58:59], off
	global_load_dword v57, v[60:61], off
	global_load_dword v74, v[62:63], off
	global_load_dword v75, v[64:65], off
	global_load_dword v76, v[66:67], off
	global_load_dword v77, v[68:69], off
	global_load_dword v78, v[70:71], off
	global_load_dword v79, v[72:73], off
	v_add_u32_e32 v58, s40, v19
	v_add_u32_e32 v60, s40, v20
	v_add_u32_e32 v62, s40, v21
	v_add_u32_e32 v64, s40, v22
	v_add_u32_e32 v66, s40, v23
	v_add_u32_e32 v68, s40, v25
	v_add_u32_e32 v70, s40, v26
	v_add_u32_e32 v72, s40, v27
	v_ashrrev_i32_e32 v59, 31, v58
	v_ashrrev_i32_e32 v61, 31, v60
	v_ashrrev_i32_e32 v63, 31, v62
	v_ashrrev_i32_e32 v65, 31, v64
	v_ashrrev_i32_e32 v67, 31, v66
	v_ashrrev_i32_e32 v69, 31, v68
	v_ashrrev_i32_e32 v71, 31, v70
	v_ashrrev_i32_e32 v73, 31, v72
	v_lshlrev_b64 v[58:59], 13, v[58:59]
	v_lshlrev_b64 v[60:61], 13, v[60:61]
	v_lshlrev_b64 v[62:63], 13, v[62:63]
	v_lshlrev_b64 v[64:65], 13, v[64:65]
	v_lshlrev_b64 v[66:67], 13, v[66:67]
	v_lshlrev_b64 v[68:69], 13, v[68:69]
	v_lshlrev_b64 v[70:71], 13, v[70:71]
	v_lshlrev_b64 v[72:73], 13, v[72:73]
	v_lshl_add_u64 v[58:59], v[6:7], 0, v[58:59]
	v_lshl_add_u64 v[60:61], v[6:7], 0, v[60:61]
	v_lshl_add_u64 v[62:63], v[6:7], 0, v[62:63]
	v_lshl_add_u64 v[64:65], v[6:7], 0, v[64:65]
	v_lshl_add_u64 v[66:67], v[6:7], 0, v[66:67]
	v_lshl_add_u64 v[68:69], v[6:7], 0, v[68:69]
	v_lshl_add_u64 v[70:71], v[6:7], 0, v[70:71]
	v_lshl_add_u64 v[72:73], v[6:7], 0, v[72:73]
	global_load_dword v80, v[58:59], off
	global_load_dword v81, v[60:61], off
	global_load_dword v82, v[62:63], off
	global_load_dword v83, v[64:65], off
	global_load_dword v84, v[66:67], off
	global_load_dword v85, v[68:69], off
	global_load_dword v86, v[70:71], off
	global_load_dword v87, v[72:73], off
	v_add_u32_e32 v58, s40, v28
	v_add_u32_e32 v60, s40, v29
	v_add_u32_e32 v62, s40, v30
	v_add_u32_e32 v64, s40, v32
	v_add_u32_e32 v66, s40, v33
	v_add_u32_e32 v68, s40, v34
	v_add_u32_e32 v70, s40, v35
	v_add_u32_e32 v72, s40, v36
	v_ashrrev_i32_e32 v59, 31, v58
	v_ashrrev_i32_e32 v61, 31, v60
	v_ashrrev_i32_e32 v63, 31, v62
	v_ashrrev_i32_e32 v65, 31, v64
	v_ashrrev_i32_e32 v67, 31, v66
	v_ashrrev_i32_e32 v69, 31, v68
	v_ashrrev_i32_e32 v71, 31, v70
	v_ashrrev_i32_e32 v73, 31, v72
	v_lshlrev_b64 v[58:59], 13, v[58:59]
	v_lshlrev_b64 v[60:61], 13, v[60:61]
	v_lshlrev_b64 v[62:63], 13, v[62:63]
	v_lshlrev_b64 v[64:65], 13, v[64:65]
	v_lshlrev_b64 v[66:67], 13, v[66:67]
	v_lshlrev_b64 v[68:69], 13, v[68:69]
	v_lshlrev_b64 v[70:71], 13, v[70:71]
	v_lshlrev_b64 v[72:73], 13, v[72:73]
	v_lshl_add_u64 v[58:59], v[6:7], 0, v[58:59]
	v_lshl_add_u64 v[60:61], v[6:7], 0, v[60:61]
	v_lshl_add_u64 v[62:63], v[6:7], 0, v[62:63]
	v_lshl_add_u64 v[64:65], v[6:7], 0, v[64:65]
	v_lshl_add_u64 v[66:67], v[6:7], 0, v[66:67]
	v_lshl_add_u64 v[68:69], v[6:7], 0, v[68:69]
	v_lshl_add_u64 v[70:71], v[6:7], 0, v[70:71]
	v_lshl_add_u64 v[72:73], v[6:7], 0, v[72:73]
	global_load_dword v88, v[58:59], off
	global_load_dword v89, v[60:61], off
	global_load_dword v90, v[62:63], off
	global_load_dword v91, v[64:65], off
	global_load_dword v92, v[66:67], off
	global_load_dword v93, v[68:69], off
	global_load_dword v94, v[70:71], off
	global_load_dword v95, v[72:73], off
	v_add_u32_e32 v58, s40, v37
	v_add_u32_e32 v60, s40, v39
	v_add_u32_e32 v62, s40, v40
	v_add_u32_e32 v64, s40, v41
	v_add_u32_e32 v66, s40, v42
	v_add_u32_e32 v68, s40, v43
	v_add_u32_e32 v70, s40, v44
	v_add_u32_e32 v72, s40, v45
	v_ashrrev_i32_e32 v59, 31, v58
	v_ashrrev_i32_e32 v61, 31, v60
	v_ashrrev_i32_e32 v63, 31, v62
	v_ashrrev_i32_e32 v65, 31, v64
	v_ashrrev_i32_e32 v67, 31, v66
	v_ashrrev_i32_e32 v69, 31, v68
	v_ashrrev_i32_e32 v71, 31, v70
	v_ashrrev_i32_e32 v73, 31, v72
	v_lshlrev_b64 v[58:59], 13, v[58:59]
	v_lshlrev_b64 v[60:61], 13, v[60:61]
	v_lshlrev_b64 v[62:63], 13, v[62:63]
	v_lshlrev_b64 v[64:65], 13, v[64:65]
	v_lshlrev_b64 v[66:67], 13, v[66:67]
	v_lshlrev_b64 v[68:69], 13, v[68:69]
	v_lshlrev_b64 v[70:71], 13, v[70:71]
	v_lshlrev_b64 v[72:73], 13, v[72:73]
	v_lshl_add_u64 v[58:59], v[6:7], 0, v[58:59]
	v_lshl_add_u64 v[60:61], v[6:7], 0, v[60:61]
	v_lshl_add_u64 v[62:63], v[6:7], 0, v[62:63]
	v_lshl_add_u64 v[64:65], v[6:7], 0, v[64:65]
	v_lshl_add_u64 v[66:67], v[6:7], 0, v[66:67]
	v_lshl_add_u64 v[68:69], v[6:7], 0, v[68:69]
	v_lshl_add_u64 v[70:71], v[6:7], 0, v[70:71]
	v_lshl_add_u64 v[6:7], v[6:7], 0, v[72:73]
	global_load_dword v58, v[58:59], off
	s_nop 0
	global_load_dword v59, v[60:61], off
	s_nop 0
	global_load_dword v60, v[62:63], off
	global_load_dword v61, v[64:65], off
	s_nop 0
	global_load_dword v62, v[66:67], off
	global_load_dword v63, v[68:69], off
	global_load_dword v64, v[70:71], off
	s_nop 0
	global_load_dword v6, v[6:7], off
	v_add_u32_e32 v7, v9, v10
	s_waitcnt vmcnt(0)
	ds_write2_b32 v7, v0, v57 offset1:66
	ds_write2_b32 v7, v74, v75 offset0:132 offset1:198
	v_add_u32_e32 v0, 0x400, v7
	ds_write2_b32 v0, v76, v77 offset0:8 offset1:74
	v_add_u32_e32 v0, v9, v17
	ds_write2_b32 v0, v78, v79 offset1:66
	ds_write2_b32 v0, v80, v81 offset0:132 offset1:198
	v_add_u32_e32 v0, 0x400, v0
	ds_write2_b32 v0, v82, v83 offset0:8 offset1:74
	v_add_u32_e32 v0, v9, v24
	ds_write2_b32 v0, v84, v85 offset1:66
	ds_write2_b32 v0, v86, v87 offset0:132 offset1:198
	v_add_u32_e32 v0, 0x400, v0
	s_lshl_b32 s40, s40, 1
	s_add_u32 s38, s38, s40
	s_addc_u32 s39, s39, 0
	ds_write2_b32 v0, v88, v89 offset0:8 offset1:74
	v_add_u32_e32 v0, v9, v31
	ds_write2_b32 v0, v90, v91 offset1:66
	ds_write2_b32 v0, v92, v93 offset0:132 offset1:198
	v_add_u32_e32 v0, 0x400, v0
	ds_write2_b32 v0, v94, v95 offset0:8 offset1:74
	v_add_u32_e32 v0, v9, v38
	ds_write2_b32 v0, v58, v59 offset1:66
	ds_write2_b32 v0, v60, v61 offset0:132 offset1:198
	v_add_u32_e32 v0, 0x400, v0
	ds_write2_b32 v0, v62, v63 offset0:8 offset1:74
	ds_write2_b32 v0, v64, v6 offset0:140 offset1:206
	s_waitcnt lgkmcnt(0)
	ds_read2_b32 v[112:113], v47 offset1:33
	ds_read2_b32 v[114:115], v47 offset0:66 offset1:99
	ds_read2_b32 v[116:117], v47 offset0:132 offset1:165
	ds_read2_b32 v[118:119], v47 offset0:198 offset1:231
	ds_read2_b32 v[120:121], v47 offset0:8 offset1:41
	ds_read2_b32 v[122:123], v47 offset0:74 offset1:107
	ds_read2_b32 v[124:125], v47 offset0:140 offset1:173
	ds_read2_b32 v[126:127], v47 offset0:206 offset1:239
	ds_read2_b32 v[128:129], v47 offset0:16 offset1:49
	ds_read2_b32 v[130:131], v47 offset0:82 offset1:115
	ds_read2_b32 v[132:133], v47 offset0:148 offset1:181
	ds_read2_b32 v[134:135], v47 offset0:214 offset1:247
	ds_read2_b32 v[136:137], v47 offset0:24 offset1:57
	ds_read2_b32 v[138:139], v47 offset0:90 offset1:123
	ds_read2_b32 v[140:141], v47 offset0:156 offset1:189
	ds_read2_b32 v[142:143], v47 offset0:222 offset1:255
	s_waitcnt lgkmcnt(0)
	v_cvt_pk_bf16_f32 v58, v112, v113
	v_cvt_pk_bf16_f32 v59, v114, v115
	v_cvt_pk_bf16_f32 v60, v116, v117
	v_cvt_pk_bf16_f32 v61, v118, v119
	v_add_u32_e32 v6, s2, v46
	v_lshlrev_b32_e32 v0, 1, v2
	v_ashrrev_i32_e32 v7, 31, v6
	v_lshl_add_u64 v[62:63], s[38:39], 0, v[0:1]
	v_lshlrev_b64 v[6:7], 12, v[6:7]
	v_lshl_add_u64 v[6:7], v[62:63], 0, v[6:7]
	global_store_dwordx4 v[6:7], v[58:61], off
	s_nop 0
	v_cvt_pk_bf16_f32 v58, v120, v121
	v_cvt_pk_bf16_f32 v59, v122, v123
	v_cvt_pk_bf16_f32 v60, v124, v125
	v_cvt_pk_bf16_f32 v61, v126, v127
	v_add_u32_e32 v6, s2, v53
	v_ashrrev_i32_e32 v7, 31, v6
	v_lshlrev_b64 v[6:7], 12, v[6:7]
	v_lshl_add_u64 v[6:7], v[62:63], 0, v[6:7]
	global_store_dwordx4 v[6:7], v[58:61], off
	s_nop 0
	v_cvt_pk_bf16_f32 v58, v128, v129
	v_cvt_pk_bf16_f32 v59, v130, v131
	v_cvt_pk_bf16_f32 v60, v132, v133
	v_cvt_pk_bf16_f32 v61, v134, v135
	v_add_u32_e32 v6, s2, v54
	v_ashrrev_i32_e32 v7, 31, v6
	v_lshlrev_b64 v[6:7], 12, v[6:7]
	v_lshl_add_u64 v[6:7], v[62:63], 0, v[6:7]
	global_store_dwordx4 v[6:7], v[58:61], off
	s_nop 0
	v_cvt_pk_bf16_f32 v58, v136, v137
	v_cvt_pk_bf16_f32 v59, v138, v139
	v_cvt_pk_bf16_f32 v60, v140, v141
	v_cvt_pk_bf16_f32 v61, v142, v143
	v_add_u32_e32 v6, s2, v55
	v_ashrrev_i32_e32 v7, 31, v6
	v_lshlrev_b64 v[6:7], 12, v[6:7]
	v_lshl_add_u64 v[6:7], v[62:63], 0, v[6:7]
	global_store_dwordx4 v[6:7], v[58:61], off
	s_waitcnt lgkmcnt(0)

.LBB0_719:
	s_andn2_b64 vcc, exec, s[38:39]
	s_cbranch_vccnz .LBB0_721
	s_add_i32 s2, s17, 0x9e00
	s_lshr_b32 s2, s2, 1
	s_and_b32 s2, s2, 0x7fc0
	s_and_b32 s38, s53, 0xfe0
	v_or_b32_e32 v0, s38, v3
	v_add_u32_e32 v58, s2, v8
	v_add_u32_e32 v60, s2, v11
	v_add_u32_e32 v62, s2, v12
	v_add_u32_e32 v64, s2, v13
	v_add_u32_e32 v66, s2, v14
	v_add_u32_e32 v68, s2, v15
	v_add_u32_e32 v70, s2, v16
	v_add_u32_e32 v72, s2, v18
	v_lshlrev_b32_e32 v0, 2, v0
	v_ashrrev_i32_e32 v59, 31, v58
	v_ashrrev_i32_e32 v61, 31, v60
	v_ashrrev_i32_e32 v63, 31, v62
	v_ashrrev_i32_e32 v65, 31, v64
	v_ashrrev_i32_e32 v67, 31, v66
	v_ashrrev_i32_e32 v69, 31, v68
	v_ashrrev_i32_e32 v71, 31, v70
	v_ashrrev_i32_e32 v73, 31, v72
	v_lshl_add_u64 v[6:7], s[24:25], 0, v[0:1]
	v_lshlrev_b64 v[58:59], 14, v[58:59]
	v_lshlrev_b64 v[60:61], 14, v[60:61]
	v_lshlrev_b64 v[62:63], 14, v[62:63]
	v_lshlrev_b64 v[64:65], 14, v[64:65]
	v_lshlrev_b64 v[66:67], 14, v[66:67]
	v_lshlrev_b64 v[68:69], 14, v[68:69]
	v_lshlrev_b64 v[70:71], 14, v[70:71]
	v_lshlrev_b64 v[72:73], 14, v[72:73]
	v_lshl_add_u64 v[58:59], v[6:7], 0, v[58:59]
	v_lshl_add_u64 v[60:61], v[6:7], 0, v[60:61]
	v_lshl_add_u64 v[62:63], v[6:7], 0, v[62:63]
	v_lshl_add_u64 v[64:65], v[6:7], 0, v[64:65]
	v_lshl_add_u64 v[66:67], v[6:7], 0, v[66:67]
	v_lshl_add_u64 v[68:69], v[6:7], 0, v[68:69]
	v_lshl_add_u64 v[70:71], v[6:7], 0, v[70:71]
	v_lshl_add_u64 v[72:73], v[6:7], 0, v[72:73]
	global_load_dword v0, v[58:59], off
	global_load_dword v57, v[60:61], off
	global_load_dword v74, v[62:63], off
	global_load_dword v75, v[64:65], off
	global_load_dword v76, v[66:67], off
	global_load_dword v77, v[68:69], off
	global_load_dword v78, v[70:71], off
	global_load_dword v79, v[72:73], off
	v_add_u32_e32 v58, s2, v19
	v_add_u32_e32 v60, s2, v20
	v_add_u32_e32 v62, s2, v21
	v_add_u32_e32 v64, s2, v22
	v_add_u32_e32 v66, s2, v23
	v_add_u32_e32 v68, s2, v25
	v_add_u32_e32 v70, s2, v26
	v_add_u32_e32 v72, s2, v27
	v_ashrrev_i32_e32 v59, 31, v58
	v_ashrrev_i32_e32 v61, 31, v60
	v_ashrrev_i32_e32 v63, 31, v62
	v_ashrrev_i32_e32 v65, 31, v64
	v_ashrrev_i32_e32 v67, 31, v66
	v_ashrrev_i32_e32 v69, 31, v68
	v_ashrrev_i32_e32 v71, 31, v70
	v_ashrrev_i32_e32 v73, 31, v72
	v_lshlrev_b64 v[58:59], 14, v[58:59]
	v_lshlrev_b64 v[60:61], 14, v[60:61]
	v_lshlrev_b64 v[62:63], 14, v[62:63]
	v_lshlrev_b64 v[64:65], 14, v[64:65]
	v_lshlrev_b64 v[66:67], 14, v[66:67]
	v_lshlrev_b64 v[68:69], 14, v[68:69]
	v_lshlrev_b64 v[70:71], 14, v[70:71]
	v_lshlrev_b64 v[72:73], 14, v[72:73]
	v_lshl_add_u64 v[58:59], v[6:7], 0, v[58:59]
	v_lshl_add_u64 v[60:61], v[6:7], 0, v[60:61]
	v_lshl_add_u64 v[62:63], v[6:7], 0, v[62:63]
	v_lshl_add_u64 v[64:65], v[6:7], 0, v[64:65]
	v_lshl_add_u64 v[66:67], v[6:7], 0, v[66:67]
	v_lshl_add_u64 v[68:69], v[6:7], 0, v[68:69]
	v_lshl_add_u64 v[70:71], v[6:7], 0, v[70:71]
	v_lshl_add_u64 v[72:73], v[6:7], 0, v[72:73]
	global_load_dword v80, v[58:59], off
	global_load_dword v81, v[60:61], off
	global_load_dword v82, v[62:63], off
	global_load_dword v83, v[64:65], off
	global_load_dword v84, v[66:67], off
	global_load_dword v85, v[68:69], off
	global_load_dword v86, v[70:71], off
	global_load_dword v87, v[72:73], off
	v_add_u32_e32 v58, s2, v28
	v_add_u32_e32 v60, s2, v29
	v_add_u32_e32 v62, s2, v30
	v_add_u32_e32 v64, s2, v32
	v_add_u32_e32 v66, s2, v33
	v_add_u32_e32 v68, s2, v34
	v_add_u32_e32 v70, s2, v35
	v_add_u32_e32 v72, s2, v36
	v_ashrrev_i32_e32 v59, 31, v58
	v_ashrrev_i32_e32 v61, 31, v60
	v_ashrrev_i32_e32 v63, 31, v62
	v_ashrrev_i32_e32 v65, 31, v64
	v_ashrrev_i32_e32 v67, 31, v66
	v_ashrrev_i32_e32 v69, 31, v68
	v_ashrrev_i32_e32 v71, 31, v70
	v_ashrrev_i32_e32 v73, 31, v72
	v_lshlrev_b64 v[58:59], 14, v[58:59]
	v_lshlrev_b64 v[60:61], 14, v[60:61]
	v_lshlrev_b64 v[62:63], 14, v[62:63]
	v_lshlrev_b64 v[64:65], 14, v[64:65]
	v_lshlrev_b64 v[66:67], 14, v[66:67]
	v_lshlrev_b64 v[68:69], 14, v[68:69]
	v_lshlrev_b64 v[70:71], 14, v[70:71]
	v_lshlrev_b64 v[72:73], 14, v[72:73]
	v_lshl_add_u64 v[58:59], v[6:7], 0, v[58:59]
	v_lshl_add_u64 v[60:61], v[6:7], 0, v[60:61]
	v_lshl_add_u64 v[62:63], v[6:7], 0, v[62:63]
	v_lshl_add_u64 v[64:65], v[6:7], 0, v[64:65]
	v_lshl_add_u64 v[66:67], v[6:7], 0, v[66:67]
	v_lshl_add_u64 v[68:69], v[6:7], 0, v[68:69]
	v_lshl_add_u64 v[70:71], v[6:7], 0, v[70:71]
	v_lshl_add_u64 v[72:73], v[6:7], 0, v[72:73]
	global_load_dword v88, v[58:59], off
	global_load_dword v89, v[60:61], off
	global_load_dword v90, v[62:63], off
	global_load_dword v91, v[64:65], off
	global_load_dword v92, v[66:67], off
	global_load_dword v93, v[68:69], off
	global_load_dword v94, v[70:71], off
	global_load_dword v95, v[72:73], off
	v_add_u32_e32 v58, s2, v37
	v_add_u32_e32 v60, s2, v39
	v_add_u32_e32 v62, s2, v40
	v_add_u32_e32 v64, s2, v41
	v_add_u32_e32 v66, s2, v42
	v_add_u32_e32 v68, s2, v43
	v_add_u32_e32 v70, s2, v44
	v_add_u32_e32 v72, s2, v45
	v_ashrrev_i32_e32 v59, 31, v58
	v_ashrrev_i32_e32 v61, 31, v60
	v_ashrrev_i32_e32 v63, 31, v62
	v_ashrrev_i32_e32 v65, 31, v64
	v_ashrrev_i32_e32 v67, 31, v66
	v_ashrrev_i32_e32 v69, 31, v68
	v_ashrrev_i32_e32 v71, 31, v70
	v_ashrrev_i32_e32 v73, 31, v72
	v_lshlrev_b64 v[58:59], 14, v[58:59]
	v_lshlrev_b64 v[60:61], 14, v[60:61]
	v_lshlrev_b64 v[62:63], 14, v[62:63]
	v_lshlrev_b64 v[64:65], 14, v[64:65]
	v_lshlrev_b64 v[66:67], 14, v[66:67]
	v_lshlrev_b64 v[68:69], 14, v[68:69]
	v_lshlrev_b64 v[70:71], 14, v[70:71]
	v_lshlrev_b64 v[72:73], 14, v[72:73]
	v_lshl_add_u64 v[58:59], v[6:7], 0, v[58:59]
	v_lshl_add_u64 v[60:61], v[6:7], 0, v[60:61]
	v_lshl_add_u64 v[62:63], v[6:7], 0, v[62:63]
	v_lshl_add_u64 v[64:65], v[6:7], 0, v[64:65]
	v_lshl_add_u64 v[66:67], v[6:7], 0, v[66:67]
	v_lshl_add_u64 v[68:69], v[6:7], 0, v[68:69]
	v_lshl_add_u64 v[70:71], v[6:7], 0, v[70:71]
	v_lshl_add_u64 v[6:7], v[6:7], 0, v[72:73]
	global_load_dword v58, v[58:59], off
	s_nop 0
	global_load_dword v59, v[60:61], off
	s_nop 0
	global_load_dword v60, v[62:63], off
	global_load_dword v61, v[64:65], off
	s_nop 0
	global_load_dword v62, v[66:67], off
	global_load_dword v63, v[68:69], off
	global_load_dword v64, v[70:71], off
	s_nop 0
	global_load_dword v6, v[6:7], off
	v_add_u32_e32 v7, v9, v10
	s_waitcnt vmcnt(0)
	ds_write2_b32 v7, v0, v57 offset1:66
	ds_write2_b32 v7, v74, v75 offset0:132 offset1:198
	v_add_u32_e32 v0, 0x400, v7
	ds_write2_b32 v0, v76, v77 offset0:8 offset1:74
	v_add_u32_e32 v0, v9, v17
	ds_write2_b32 v0, v78, v79 offset1:66
	ds_write2_b32 v0, v80, v81 offset0:132 offset1:198
	v_add_u32_e32 v0, 0x400, v0
	ds_write2_b32 v0, v82, v83 offset0:8 offset1:74
	v_add_u32_e32 v0, v9, v24
	ds_write2_b32 v0, v84, v85 offset1:66
	ds_write2_b32 v0, v86, v87 offset0:132 offset1:198
	v_add_u32_e32 v0, 0x400, v0
	s_lshl_b32 s2, s2, 1
	ds_write2_b32 v0, v88, v89 offset0:8 offset1:74
	v_add_u32_e32 v0, v9, v31
	ds_write2_b32 v0, v90, v91 offset1:66
	ds_write2_b32 v0, v92, v93 offset0:132 offset1:198
	v_add_u32_e32 v0, 0x400, v0
	ds_write2_b32 v0, v94, v95 offset0:8 offset1:74
	v_add_u32_e32 v0, v9, v38
	ds_write2_b32 v0, v58, v59 offset1:66
	ds_write2_b32 v0, v60, v61 offset0:132 offset1:198
	v_add_u32_e32 v0, 0x400, v0
	ds_write2_b32 v0, v62, v63 offset0:8 offset1:74
	ds_write2_b32 v0, v64, v6 offset0:140 offset1:206
	s_waitcnt lgkmcnt(0)
	ds_read2_b32 v[112:113], v47 offset1:33
	ds_read2_b32 v[114:115], v47 offset0:66 offset1:99
	ds_read2_b32 v[116:117], v47 offset0:132 offset1:165
	ds_read2_b32 v[118:119], v47 offset0:198 offset1:231
	ds_read2_b32 v[120:121], v47 offset0:8 offset1:41
	ds_read2_b32 v[122:123], v47 offset0:74 offset1:107
	ds_read2_b32 v[124:125], v47 offset0:140 offset1:173
	ds_read2_b32 v[126:127], v47 offset0:206 offset1:239
	ds_read2_b32 v[128:129], v47 offset0:16 offset1:49
	ds_read2_b32 v[130:131], v47 offset0:82 offset1:115
	ds_read2_b32 v[132:133], v47 offset0:148 offset1:181
	ds_read2_b32 v[134:135], v47 offset0:214 offset1:247
	ds_read2_b32 v[136:137], v47 offset0:24 offset1:57
	ds_read2_b32 v[138:139], v47 offset0:90 offset1:123
	ds_read2_b32 v[140:141], v47 offset0:156 offset1:189
	ds_read2_b32 v[142:143], v47 offset0:222 offset1:255
	s_waitcnt lgkmcnt(0)
	v_cvt_pk_bf16_f32 v58, v112, v113
	v_cvt_pk_bf16_f32 v59, v114, v115
	v_cvt_pk_bf16_f32 v60, v116, v117
	v_cvt_pk_bf16_f32 v61, v118, v119
	v_add_u32_e32 v6, s38, v46
	v_ashrrev_i32_e32 v7, 31, v6
	v_lshl_add_u64 v[62:63], v[4:5], 0, s[2:3]
	v_lshlrev_b64 v[6:7], 12, v[6:7]
	v_lshl_add_u64 v[6:7], v[62:63], 0, v[6:7]
	global_store_dwordx4 v[6:7], v[58:61], off
	s_nop 0
	v_cvt_pk_bf16_f32 v58, v120, v121
	v_cvt_pk_bf16_f32 v59, v122, v123
	v_cvt_pk_bf16_f32 v60, v124, v125
	v_cvt_pk_bf16_f32 v61, v126, v127
	v_add_u32_e32 v6, s38, v53
	v_ashrrev_i32_e32 v7, 31, v6
	v_lshlrev_b64 v[6:7], 12, v[6:7]
	v_lshl_add_u64 v[6:7], v[62:63], 0, v[6:7]
	global_store_dwordx4 v[6:7], v[58:61], off
	s_nop 0
	v_cvt_pk_bf16_f32 v58, v128, v129
	v_cvt_pk_bf16_f32 v59, v130, v131
	v_cvt_pk_bf16_f32 v60, v132, v133
	v_cvt_pk_bf16_f32 v61, v134, v135
	v_add_u32_e32 v6, s38, v54
	v_ashrrev_i32_e32 v7, 31, v6
	v_lshlrev_b64 v[6:7], 12, v[6:7]
	v_lshl_add_u64 v[6:7], v[62:63], 0, v[6:7]
	global_store_dwordx4 v[6:7], v[58:61], off
	s_nop 0
	v_cvt_pk_bf16_f32 v58, v136, v137
	v_cvt_pk_bf16_f32 v59, v138, v139
	v_cvt_pk_bf16_f32 v60, v140, v141
	v_cvt_pk_bf16_f32 v61, v142, v143
	v_add_u32_e32 v6, s38, v55
	v_ashrrev_i32_e32 v7, 31, v6
	v_lshlrev_b64 v[6:7], 12, v[6:7]
	v_lshl_add_u64 v[6:7], v[62:63], 0, v[6:7]
	global_store_dwordx4 v[6:7], v[58:61], off
	s_waitcnt lgkmcnt(0)

.LBB0_722:
	s_andn2_b64 vcc, exec, s[38:39]
	s_cbranch_vccnz .LBB0_724
	s_add_i32 s40, s17, 0xffffbe00
	s_lshr_b32 s2, s40, 12
	s_lshl_b64 s[38:39], s[2:3], 25
	s_add_u32 s42, s28, s38
	s_addc_u32 s43, s29, s39
	s_lshl_b64 s[38:39], s[2:3], 24
	s_add_u32 s38, s49, s38
	s_addc_u32 s39, s50, s39
	s_lshr_b32 s2, s40, 1
	s_and_b32 s40, s2, 0x7c0
	s_and_b32 s2, s53, 0xfe0
	v_or_b32_e32 v0, s2, v3
	v_add_u32_e32 v58, s40, v8
	v_add_u32_e32 v60, s40, v11
	v_add_u32_e32 v62, s40, v12
	v_add_u32_e32 v64, s40, v13
	v_add_u32_e32 v66, s40, v14
	v_add_u32_e32 v68, s40, v15
	v_add_u32_e32 v70, s40, v16
	v_add_u32_e32 v72, s40, v18
	v_lshlrev_b32_e32 v0, 2, v0
	v_ashrrev_i32_e32 v59, 31, v58
	v_ashrrev_i32_e32 v61, 31, v60
	v_ashrrev_i32_e32 v63, 31, v62
	v_ashrrev_i32_e32 v65, 31, v64
	v_ashrrev_i32_e32 v67, 31, v66
	v_ashrrev_i32_e32 v69, 31, v68
	v_ashrrev_i32_e32 v71, 31, v70
	v_ashrrev_i32_e32 v73, 31, v72
	v_lshl_add_u64 v[6:7], s[42:43], 0, v[0:1]
	v_lshlrev_b64 v[58:59], 14, v[58:59]
	v_lshlrev_b64 v[60:61], 14, v[60:61]
	v_lshlrev_b64 v[62:63], 14, v[62:63]
	v_lshlrev_b64 v[64:65], 14, v[64:65]
	v_lshlrev_b64 v[66:67], 14, v[66:67]
	v_lshlrev_b64 v[68:69], 14, v[68:69]
	v_lshlrev_b64 v[70:71], 14, v[70:71]
	v_lshlrev_b64 v[72:73], 14, v[72:73]
	v_lshl_add_u64 v[58:59], v[6:7], 0, v[58:59]
	v_lshl_add_u64 v[60:61], v[6:7], 0, v[60:61]
	v_lshl_add_u64 v[62:63], v[6:7], 0, v[62:63]
	v_lshl_add_u64 v[64:65], v[6:7], 0, v[64:65]
	v_lshl_add_u64 v[66:67], v[6:7], 0, v[66:67]
	v_lshl_add_u64 v[68:69], v[6:7], 0, v[68:69]
	v_lshl_add_u64 v[70:71], v[6:7], 0, v[70:71]
	v_lshl_add_u64 v[72:73], v[6:7], 0, v[72:73]
	global_load_dword v0, v[58:59], off
	global_load_dword v57, v[60:61], off
	global_load_dword v74, v[62:63], off
	global_load_dword v75, v[64:65], off
	global_load_dword v76, v[66:67], off
	global_load_dword v77, v[68:69], off
	global_load_dword v78, v[70:71], off
	global_load_dword v79, v[72:73], off
	v_add_u32_e32 v58, s40, v19
	v_add_u32_e32 v60, s40, v20
	v_add_u32_e32 v62, s40, v21
	v_add_u32_e32 v64, s40, v22
	v_add_u32_e32 v66, s40, v23
	v_add_u32_e32 v68, s40, v25
	v_add_u32_e32 v70, s40, v26
	v_add_u32_e32 v72, s40, v27
	v_ashrrev_i32_e32 v59, 31, v58
	v_ashrrev_i32_e32 v61, 31, v60
	v_ashrrev_i32_e32 v63, 31, v62
	v_ashrrev_i32_e32 v65, 31, v64
	v_ashrrev_i32_e32 v67, 31, v66
	v_ashrrev_i32_e32 v69, 31, v68
	v_ashrrev_i32_e32 v71, 31, v70
	v_ashrrev_i32_e32 v73, 31, v72
	v_lshlrev_b64 v[58:59], 14, v[58:59]
	v_lshlrev_b64 v[60:61], 14, v[60:61]
	v_lshlrev_b64 v[62:63], 14, v[62:63]
	v_lshlrev_b64 v[64:65], 14, v[64:65]
	v_lshlrev_b64 v[66:67], 14, v[66:67]
	v_lshlrev_b64 v[68:69], 14, v[68:69]
	v_lshlrev_b64 v[70:71], 14, v[70:71]
	v_lshlrev_b64 v[72:73], 14, v[72:73]
	v_lshl_add_u64 v[58:59], v[6:7], 0, v[58:59]
	v_lshl_add_u64 v[60:61], v[6:7], 0, v[60:61]
	v_lshl_add_u64 v[62:63], v[6:7], 0, v[62:63]
	v_lshl_add_u64 v[64:65], v[6:7], 0, v[64:65]
	v_lshl_add_u64 v[66:67], v[6:7], 0, v[66:67]
	v_lshl_add_u64 v[68:69], v[6:7], 0, v[68:69]
	v_lshl_add_u64 v[70:71], v[6:7], 0, v[70:71]
	v_lshl_add_u64 v[72:73], v[6:7], 0, v[72:73]
	global_load_dword v80, v[58:59], off
	global_load_dword v81, v[60:61], off
	global_load_dword v82, v[62:63], off
	global_load_dword v83, v[64:65], off
	global_load_dword v84, v[66:67], off
	global_load_dword v85, v[68:69], off
	global_load_dword v86, v[70:71], off
	global_load_dword v87, v[72:73], off
	v_add_u32_e32 v58, s40, v28
	v_add_u32_e32 v60, s40, v29
	v_add_u32_e32 v62, s40, v30
	v_add_u32_e32 v64, s40, v32
	v_add_u32_e32 v66, s40, v33
	v_add_u32_e32 v68, s40, v34
	v_add_u32_e32 v70, s40, v35
	v_add_u32_e32 v72, s40, v36
	v_ashrrev_i32_e32 v59, 31, v58
	v_ashrrev_i32_e32 v61, 31, v60
	v_ashrrev_i32_e32 v63, 31, v62
	v_ashrrev_i32_e32 v65, 31, v64
	v_ashrrev_i32_e32 v67, 31, v66
	v_ashrrev_i32_e32 v69, 31, v68
	v_ashrrev_i32_e32 v71, 31, v70
	v_ashrrev_i32_e32 v73, 31, v72
	v_lshlrev_b64 v[58:59], 14, v[58:59]
	v_lshlrev_b64 v[60:61], 14, v[60:61]
	v_lshlrev_b64 v[62:63], 14, v[62:63]
	v_lshlrev_b64 v[64:65], 14, v[64:65]
	v_lshlrev_b64 v[66:67], 14, v[66:67]
	v_lshlrev_b64 v[68:69], 14, v[68:69]
	v_lshlrev_b64 v[70:71], 14, v[70:71]
	v_lshlrev_b64 v[72:73], 14, v[72:73]
	v_lshl_add_u64 v[58:59], v[6:7], 0, v[58:59]
	v_lshl_add_u64 v[60:61], v[6:7], 0, v[60:61]
	v_lshl_add_u64 v[62:63], v[6:7], 0, v[62:63]
	v_lshl_add_u64 v[64:65], v[6:7], 0, v[64:65]
	v_lshl_add_u64 v[66:67], v[6:7], 0, v[66:67]
	v_lshl_add_u64 v[68:69], v[6:7], 0, v[68:69]
	v_lshl_add_u64 v[70:71], v[6:7], 0, v[70:71]
	v_lshl_add_u64 v[72:73], v[6:7], 0, v[72:73]
	global_load_dword v88, v[58:59], off
	global_load_dword v89, v[60:61], off
	global_load_dword v90, v[62:63], off
	global_load_dword v91, v[64:65], off
	global_load_dword v92, v[66:67], off
	global_load_dword v93, v[68:69], off
	global_load_dword v94, v[70:71], off
	global_load_dword v95, v[72:73], off
	v_add_u32_e32 v58, s40, v37
	v_add_u32_e32 v60, s40, v39
	v_add_u32_e32 v62, s40, v40
	v_add_u32_e32 v64, s40, v41
	v_add_u32_e32 v66, s40, v42
	v_add_u32_e32 v68, s40, v43
	v_add_u32_e32 v70, s40, v44
	v_add_u32_e32 v72, s40, v45
	v_ashrrev_i32_e32 v59, 31, v58
	v_ashrrev_i32_e32 v61, 31, v60
	v_ashrrev_i32_e32 v63, 31, v62
	v_ashrrev_i32_e32 v65, 31, v64
	v_ashrrev_i32_e32 v67, 31, v66
	v_ashrrev_i32_e32 v69, 31, v68
	v_ashrrev_i32_e32 v71, 31, v70
	v_ashrrev_i32_e32 v73, 31, v72
	v_lshlrev_b64 v[58:59], 14, v[58:59]
	v_lshlrev_b64 v[60:61], 14, v[60:61]
	v_lshlrev_b64 v[62:63], 14, v[62:63]
	v_lshlrev_b64 v[64:65], 14, v[64:65]
	v_lshlrev_b64 v[66:67], 14, v[66:67]
	v_lshlrev_b64 v[68:69], 14, v[68:69]
	v_lshlrev_b64 v[70:71], 14, v[70:71]
	v_lshlrev_b64 v[72:73], 14, v[72:73]
	v_lshl_add_u64 v[58:59], v[6:7], 0, v[58:59]
	v_lshl_add_u64 v[60:61], v[6:7], 0, v[60:61]
	v_lshl_add_u64 v[62:63], v[6:7], 0, v[62:63]
	v_lshl_add_u64 v[64:65], v[6:7], 0, v[64:65]
	v_lshl_add_u64 v[66:67], v[6:7], 0, v[66:67]
	v_lshl_add_u64 v[68:69], v[6:7], 0, v[68:69]
	v_lshl_add_u64 v[70:71], v[6:7], 0, v[70:71]
	v_lshl_add_u64 v[6:7], v[6:7], 0, v[72:73]
	global_load_dword v58, v[58:59], off
	s_nop 0
	global_load_dword v59, v[60:61], off
	s_nop 0
	global_load_dword v60, v[62:63], off
	global_load_dword v61, v[64:65], off
	s_nop 0
	global_load_dword v62, v[66:67], off
	global_load_dword v63, v[68:69], off
	global_load_dword v64, v[70:71], off
	s_nop 0
	global_load_dword v6, v[6:7], off
	v_add_u32_e32 v7, v9, v10
	s_waitcnt vmcnt(0)
	ds_write2_b32 v7, v0, v57 offset1:66
	ds_write2_b32 v7, v74, v75 offset0:132 offset1:198
	v_add_u32_e32 v0, 0x400, v7
	ds_write2_b32 v0, v76, v77 offset0:8 offset1:74
	v_add_u32_e32 v0, v9, v17
	ds_write2_b32 v0, v78, v79 offset1:66
	ds_write2_b32 v0, v80, v81 offset0:132 offset1:198
	v_add_u32_e32 v0, 0x400, v0
	ds_write2_b32 v0, v82, v83 offset0:8 offset1:74
	v_add_u32_e32 v0, v9, v24
	ds_write2_b32 v0, v84, v85 offset1:66
	ds_write2_b32 v0, v86, v87 offset0:132 offset1:198
	v_add_u32_e32 v0, 0x400, v0
	s_lshl_b32 s40, s40, 1
	s_add_u32 s38, s38, s40
	s_addc_u32 s39, s39, 0
	ds_write2_b32 v0, v88, v89 offset0:8 offset1:74
	v_add_u32_e32 v0, v9, v31
	ds_write2_b32 v0, v90, v91 offset1:66
	ds_write2_b32 v0, v92, v93 offset0:132 offset1:198
	v_add_u32_e32 v0, 0x400, v0
	ds_write2_b32 v0, v94, v95 offset0:8 offset1:74
	v_add_u32_e32 v0, v9, v38
	ds_write2_b32 v0, v58, v59 offset1:66
	ds_write2_b32 v0, v60, v61 offset0:132 offset1:198
	v_add_u32_e32 v0, 0x400, v0
	ds_write2_b32 v0, v62, v63 offset0:8 offset1:74
	ds_write2_b32 v0, v64, v6 offset0:140 offset1:206
	s_waitcnt lgkmcnt(0)
	ds_read2_b32 v[112:113], v47 offset1:33
	ds_read2_b32 v[114:115], v47 offset0:66 offset1:99
	ds_read2_b32 v[116:117], v47 offset0:132 offset1:165
	ds_read2_b32 v[118:119], v47 offset0:198 offset1:231
	ds_read2_b32 v[120:121], v47 offset0:8 offset1:41
	ds_read2_b32 v[122:123], v47 offset0:74 offset1:107
	ds_read2_b32 v[124:125], v47 offset0:140 offset1:173
	ds_read2_b32 v[126:127], v47 offset0:206 offset1:239
	ds_read2_b32 v[128:129], v47 offset0:16 offset1:49
	ds_read2_b32 v[130:131], v47 offset0:82 offset1:115
	ds_read2_b32 v[132:133], v47 offset0:148 offset1:181
	ds_read2_b32 v[134:135], v47 offset0:214 offset1:247
	ds_read2_b32 v[136:137], v47 offset0:24 offset1:57
	ds_read2_b32 v[138:139], v47 offset0:90 offset1:123
	ds_read2_b32 v[140:141], v47 offset0:156 offset1:189
	ds_read2_b32 v[142:143], v47 offset0:222 offset1:255
	s_waitcnt lgkmcnt(0)
	v_cvt_pk_bf16_f32 v58, v112, v113
	v_cvt_pk_bf16_f32 v59, v114, v115
	v_cvt_pk_bf16_f32 v60, v116, v117
	v_cvt_pk_bf16_f32 v61, v118, v119
	v_add_u32_e32 v6, s2, v46
	v_lshlrev_b32_e32 v0, 1, v2
	v_ashrrev_i32_e32 v7, 31, v6
	v_lshl_add_u64 v[62:63], s[38:39], 0, v[0:1]
	v_lshlrev_b64 v[6:7], 12, v[6:7]
	v_lshl_add_u64 v[6:7], v[62:63], 0, v[6:7]
	global_store_dwordx4 v[6:7], v[58:61], off
	s_nop 0
	v_cvt_pk_bf16_f32 v58, v120, v121
	v_cvt_pk_bf16_f32 v59, v122, v123
	v_cvt_pk_bf16_f32 v60, v124, v125
	v_cvt_pk_bf16_f32 v61, v126, v127
	v_add_u32_e32 v6, s2, v53
	v_ashrrev_i32_e32 v7, 31, v6
	v_lshlrev_b64 v[6:7], 12, v[6:7]
	v_lshl_add_u64 v[6:7], v[62:63], 0, v[6:7]
	global_store_dwordx4 v[6:7], v[58:61], off
	s_nop 0
	v_cvt_pk_bf16_f32 v58, v128, v129
	v_cvt_pk_bf16_f32 v59, v130, v131
	v_cvt_pk_bf16_f32 v60, v132, v133
	v_cvt_pk_bf16_f32 v61, v134, v135
	v_add_u32_e32 v6, s2, v54
	v_ashrrev_i32_e32 v7, 31, v6
	v_lshlrev_b64 v[6:7], 12, v[6:7]
	v_lshl_add_u64 v[6:7], v[62:63], 0, v[6:7]
	global_store_dwordx4 v[6:7], v[58:61], off
	s_nop 0
	v_cvt_pk_bf16_f32 v58, v136, v137
	v_cvt_pk_bf16_f32 v59, v138, v139
	v_cvt_pk_bf16_f32 v60, v140, v141
	v_cvt_pk_bf16_f32 v61, v142, v143
	v_add_u32_e32 v6, s2, v55
	v_ashrrev_i32_e32 v7, 31, v6
	v_lshlrev_b64 v[6:7], 12, v[6:7]
	v_lshl_add_u64 v[6:7], v[62:63], 0, v[6:7]
	global_store_dwordx4 v[6:7], v[58:61], off
	s_waitcnt lgkmcnt(0)

.LBB0_725:
	s_andn2_b64 vcc, exec, s[38:39]
	s_cbranch_vccnz .LBB0_727
	s_add_i32 s40, s17, 0xffffce00
	s_and_b32 s2, s40, 0xfffff800
	s_lshl_b64 s[38:39], s[2:3], 13
	s_add_u32 s42, s30, s38
	s_addc_u32 s43, s31, s39
	s_lshl_b64 s[38:39], s[2:3], 12
	s_add_u32 s38, s51, s38
	s_addc_u32 s39, s52, s39
	s_and_b32 s40, s40, 0x7c0
	s_and_b32 s2, s53, 0x7e0
	v_or_b32_e32 v0, s2, v3
	v_add_u32_e32 v58, s40, v8
	v_lshlrev_b32_e32 v0, 2, v0
	v_ashrrev_i32_e32 v59, 31, v58
	v_add_u32_e32 v60, s40, v11
	v_add_u32_e32 v62, s40, v12
	v_add_u32_e32 v64, s40, v13
	v_add_u32_e32 v66, s40, v14
	v_add_u32_e32 v68, s40, v15
	v_add_u32_e32 v70, s40, v16
	v_add_u32_e32 v72, s40, v18
	v_lshl_add_u64 v[6:7], s[42:43], 0, v[0:1]
	v_lshlrev_b64 v[58:59], 13, v[58:59]
	v_ashrrev_i32_e32 v61, 31, v60
	v_ashrrev_i32_e32 v63, 31, v62
	v_ashrrev_i32_e32 v65, 31, v64
	v_ashrrev_i32_e32 v67, 31, v66
	v_ashrrev_i32_e32 v69, 31, v68
	v_ashrrev_i32_e32 v71, 31, v70
	v_ashrrev_i32_e32 v73, 31, v72
	v_lshl_add_u64 v[58:59], v[6:7], 0, v[58:59]
	v_lshlrev_b64 v[60:61], 13, v[60:61]
	v_lshlrev_b64 v[62:63], 13, v[62:63]
	v_lshlrev_b64 v[64:65], 13, v[64:65]
	v_lshlrev_b64 v[66:67], 13, v[66:67]
	v_lshlrev_b64 v[68:69], 13, v[68:69]
	v_lshlrev_b64 v[70:71], 13, v[70:71]
	v_lshlrev_b64 v[72:73], 13, v[72:73]
	v_lshl_add_u64 v[60:61], v[6:7], 0, v[60:61]
	v_lshl_add_u64 v[62:63], v[6:7], 0, v[62:63]
	v_lshl_add_u64 v[64:65], v[6:7], 0, v[64:65]
	v_lshl_add_u64 v[66:67], v[6:7], 0, v[66:67]
	v_lshl_add_u64 v[68:69], v[6:7], 0, v[68:69]
	v_lshl_add_u64 v[70:71], v[6:7], 0, v[70:71]
	v_lshl_add_u64 v[72:73], v[6:7], 0, v[72:73]
	global_load_dword v0, v[58:59], off
	global_load_dword v57, v[60:61], off
	global_load_dword v106, v[62:63], off
	global_load_dword v107, v[64:65], off
	global_load_dword v108, v[66:67], off
	global_load_dword v109, v[68:69], off
	global_load_dword v110, v[70:71], off
	global_load_dword v111, v[72:73], off
	v_add_u32_e32 v74, s40, v19
	v_add_u32_e32 v76, s40, v20
	v_add_u32_e32 v78, s40, v21
	v_add_u32_e32 v80, s40, v22
	v_add_u32_e32 v82, s40, v23
	v_add_u32_e32 v84, s40, v25
	v_add_u32_e32 v86, s40, v26
	v_add_u32_e32 v88, s40, v27
	v_add_u32_e32 v90, s40, v28
	v_add_u32_e32 v58, s40, v29
	v_add_u32_e32 v60, s40, v30
	v_add_u32_e32 v62, s40, v32
	v_add_u32_e32 v64, s40, v33
	v_add_u32_e32 v66, s40, v34
	v_add_u32_e32 v68, s40, v35
	v_add_u32_e32 v70, s40, v36
	v_add_u32_e32 v72, s40, v37
	v_add_u32_e32 v92, s40, v39
	v_add_u32_e32 v94, s40, v40
	v_add_u32_e32 v96, s40, v41
	v_add_u32_e32 v98, s40, v42
	v_add_u32_e32 v100, s40, v43
	v_add_u32_e32 v102, s40, v44
	v_add_u32_e32 v104, s40, v45
	v_ashrrev_i32_e32 v75, 31, v74
	v_ashrrev_i32_e32 v77, 31, v76
	v_ashrrev_i32_e32 v79, 31, v78
	v_ashrrev_i32_e32 v81, 31, v80
	v_ashrrev_i32_e32 v83, 31, v82
	v_ashrrev_i32_e32 v85, 31, v84
	v_ashrrev_i32_e32 v87, 31, v86
	v_ashrrev_i32_e32 v89, 31, v88
	v_ashrrev_i32_e32 v91, 31, v90
	v_ashrrev_i32_e32 v59, 31, v58
	v_ashrrev_i32_e32 v61, 31, v60
	v_ashrrev_i32_e32 v63, 31, v62
	v_ashrrev_i32_e32 v65, 31, v64
	v_ashrrev_i32_e32 v67, 31, v66
	v_ashrrev_i32_e32 v69, 31, v68
	v_ashrrev_i32_e32 v71, 31, v70
	v_ashrrev_i32_e32 v73, 31, v72
	v_ashrrev_i32_e32 v93, 31, v92
	v_ashrrev_i32_e32 v95, 31, v94
	v_ashrrev_i32_e32 v97, 31, v96
	v_ashrrev_i32_e32 v99, 31, v98
	v_ashrrev_i32_e32 v101, 31, v100
	v_ashrrev_i32_e32 v103, 31, v102
	v_ashrrev_i32_e32 v105, 31, v104
	v_lshlrev_b64 v[74:75], 13, v[74:75]
	v_lshlrev_b64 v[76:77], 13, v[76:77]
	v_lshlrev_b64 v[78:79], 13, v[78:79]
	v_lshlrev_b64 v[80:81], 13, v[80:81]
	v_lshlrev_b64 v[82:83], 13, v[82:83]
	v_lshlrev_b64 v[84:85], 13, v[84:85]
	v_lshlrev_b64 v[86:87], 13, v[86:87]
	v_lshlrev_b64 v[88:89], 13, v[88:89]
	v_lshlrev_b64 v[90:91], 13, v[90:91]
	v_lshlrev_b64 v[58:59], 13, v[58:59]
	v_lshlrev_b64 v[60:61], 13, v[60:61]
	v_lshlrev_b64 v[62:63], 13, v[62:63]
	v_lshlrev_b64 v[64:65], 13, v[64:65]
	v_lshlrev_b64 v[66:67], 13, v[66:67]
	v_lshlrev_b64 v[68:69], 13, v[68:69]
	v_lshlrev_b64 v[70:71], 13, v[70:71]
	v_lshlrev_b64 v[72:73], 13, v[72:73]
	v_lshlrev_b64 v[92:93], 13, v[92:93]
	v_lshlrev_b64 v[94:95], 13, v[94:95]
	v_lshlrev_b64 v[96:97], 13, v[96:97]
	v_lshlrev_b64 v[98:99], 13, v[98:99]
	v_lshlrev_b64 v[100:101], 13, v[100:101]
	v_lshlrev_b64 v[102:103], 13, v[102:103]
	v_lshlrev_b64 v[104:105], 13, v[104:105]
	v_lshl_add_u64 v[74:75], v[6:7], 0, v[74:75]
	v_lshl_add_u64 v[76:77], v[6:7], 0, v[76:77]
	v_lshl_add_u64 v[78:79], v[6:7], 0, v[78:79]
	v_lshl_add_u64 v[80:81], v[6:7], 0, v[80:81]
	v_lshl_add_u64 v[82:83], v[6:7], 0, v[82:83]
	v_lshl_add_u64 v[84:85], v[6:7], 0, v[84:85]
	v_lshl_add_u64 v[86:87], v[6:7], 0, v[86:87]
	v_lshl_add_u64 v[88:89], v[6:7], 0, v[88:89]
	v_lshl_add_u64 v[90:91], v[6:7], 0, v[90:91]
	v_lshl_add_u64 v[58:59], v[6:7], 0, v[58:59]
	v_lshl_add_u64 v[60:61], v[6:7], 0, v[60:61]
	v_lshl_add_u64 v[62:63], v[6:7], 0, v[62:63]
	v_lshl_add_u64 v[64:65], v[6:7], 0, v[64:65]
	v_lshl_add_u64 v[66:67], v[6:7], 0, v[66:67]
	v_lshl_add_u64 v[68:69], v[6:7], 0, v[68:69]
	v_lshl_add_u64 v[70:71], v[6:7], 0, v[70:71]
	v_lshl_add_u64 v[72:73], v[6:7], 0, v[72:73]
	v_lshl_add_u64 v[92:93], v[6:7], 0, v[92:93]
	v_lshl_add_u64 v[94:95], v[6:7], 0, v[94:95]
	v_lshl_add_u64 v[96:97], v[6:7], 0, v[96:97]
	v_lshl_add_u64 v[98:99], v[6:7], 0, v[98:99]
	v_lshl_add_u64 v[100:101], v[6:7], 0, v[100:101]
	v_lshl_add_u64 v[102:103], v[6:7], 0, v[102:103]
	v_lshl_add_u64 v[6:7], v[6:7], 0, v[104:105]
	global_load_dword v74, v[74:75], off
	s_nop 0
	global_load_dword v75, v[76:77], off
	s_nop 0
	global_load_dword v76, v[78:79], off
	global_load_dword v77, v[80:81], off
	s_nop 0
	global_load_dword v78, v[82:83], off
	global_load_dword v79, v[84:85], off
	global_load_dword v80, v[86:87], off
	global_load_dword v81, v[88:89], off
	s_nop 0
	global_load_dword v82, v[90:91], off
	s_nop 0
	global_load_dword v58, v[58:59], off
	s_nop 0
	global_load_dword v59, v[60:61], off
	s_nop 0
	global_load_dword v60, v[62:63], off
	global_load_dword v61, v[64:65], off
	s_nop 0
	global_load_dword v62, v[66:67], off
	global_load_dword v63, v[68:69], off
	global_load_dword v64, v[70:71], off
	global_load_dword v65, v[72:73], off
	s_nop 0
	global_load_dword v66, v[92:93], off
	global_load_dword v67, v[94:95], off
	global_load_dword v68, v[96:97], off
	global_load_dword v69, v[98:99], off
	global_load_dword v70, v[100:101], off
	global_load_dword v71, v[102:103], off
	s_nop 0
	global_load_dword v6, v[6:7], off
	v_add_u32_e32 v7, v9, v10
	s_waitcnt vmcnt(0)
	ds_write2_b32 v7, v0, v57 offset1:66
	ds_write2_b32 v7, v106, v107 offset0:132 offset1:198
	v_add_u32_e32 v0, 0x400, v7
	ds_write2_b32 v0, v108, v109 offset0:8 offset1:74
	v_add_u32_e32 v0, v9, v17
	ds_write2_b32 v0, v110, v111 offset1:66
	ds_write2_b32 v0, v74, v75 offset0:132 offset1:198
	v_add_u32_e32 v0, 0x400, v0
	ds_write2_b32 v0, v76, v77 offset0:8 offset1:74
	v_add_u32_e32 v0, v9, v24
	ds_write2_b32 v0, v78, v79 offset1:66
	ds_write2_b32 v0, v80, v81 offset0:132 offset1:198
	v_add_u32_e32 v0, 0x400, v0
	ds_write2_b32 v0, v82, v58 offset0:8 offset1:74
	v_add_u32_e32 v0, v9, v31
	ds_write2_b32 v0, v59, v60 offset1:66
	ds_write2_b32 v0, v61, v62 offset0:132 offset1:198
	v_add_u32_e32 v0, 0x400, v0
	ds_write2_b32 v0, v63, v64 offset0:8 offset1:74
	v_add_u32_e32 v0, v9, v38
	ds_write2_b32 v0, v65, v66 offset1:66
	ds_write2_b32 v0, v67, v68 offset0:132 offset1:198
	v_add_u32_e32 v0, 0x400, v0
	ds_write2_b32 v0, v69, v70 offset0:8 offset1:74
	ds_write2_b32 v0, v71, v6 offset0:140 offset1:206
	s_waitcnt lgkmcnt(0)
	ds_read2_b32 v[112:113], v47 offset1:33
	ds_read2_b32 v[114:115], v47 offset0:66 offset1:99
	ds_read2_b32 v[116:117], v47 offset0:132 offset1:165
	ds_read2_b32 v[118:119], v47 offset0:198 offset1:231
	ds_read2_b32 v[120:121], v47 offset0:8 offset1:41
	ds_read2_b32 v[122:123], v47 offset0:74 offset1:107
	ds_read2_b32 v[124:125], v47 offset0:140 offset1:173
	ds_read2_b32 v[126:127], v47 offset0:206 offset1:239
	ds_read2_b32 v[128:129], v47 offset0:16 offset1:49
	ds_read2_b32 v[130:131], v47 offset0:82 offset1:115
	ds_read2_b32 v[132:133], v47 offset0:148 offset1:181
	ds_read2_b32 v[134:135], v47 offset0:214 offset1:247
	ds_read2_b32 v[136:137], v47 offset0:24 offset1:57
	ds_read2_b32 v[138:139], v47 offset0:90 offset1:123
	ds_read2_b32 v[140:141], v47 offset0:156 offset1:189
	ds_read2_b32 v[142:143], v47 offset0:222 offset1:255
	s_waitcnt lgkmcnt(0)
	v_cvt_pk_bf16_f32 v58, v112, v113
	v_cvt_pk_bf16_f32 v59, v114, v115
	s_lshl_b32 s40, s40, 1
	v_cvt_pk_bf16_f32 v60, v116, v117
	s_add_u32 s38, s38, s40
	v_cvt_pk_bf16_f32 v61, v118, v119
	v_add_u32_e32 v6, s2, v46
	s_addc_u32 s39, s39, 0
	v_lshlrev_b32_e32 v0, 1, v2
	v_ashrrev_i32_e32 v7, 31, v6
	v_lshl_add_u64 v[62:63], s[38:39], 0, v[0:1]
	v_lshlrev_b64 v[6:7], 12, v[6:7]
	v_lshl_add_u64 v[6:7], v[62:63], 0, v[6:7]
	global_store_dwordx4 v[6:7], v[58:61], off
	s_nop 0
	v_cvt_pk_bf16_f32 v58, v120, v121
	v_cvt_pk_bf16_f32 v59, v122, v123
	v_cvt_pk_bf16_f32 v60, v124, v125
	v_cvt_pk_bf16_f32 v61, v126, v127
	v_add_u32_e32 v6, s2, v53
	v_ashrrev_i32_e32 v7, 31, v6
	v_lshlrev_b64 v[6:7], 12, v[6:7]
	v_lshl_add_u64 v[6:7], v[62:63], 0, v[6:7]
	global_store_dwordx4 v[6:7], v[58:61], off
	s_nop 0
	v_cvt_pk_bf16_f32 v58, v128, v129
	v_cvt_pk_bf16_f32 v59, v130, v131
	v_cvt_pk_bf16_f32 v60, v132, v133
	v_cvt_pk_bf16_f32 v61, v134, v135
	v_add_u32_e32 v6, s2, v54
	v_ashrrev_i32_e32 v7, 31, v6
	v_lshlrev_b64 v[6:7], 12, v[6:7]
	v_lshl_add_u64 v[6:7], v[62:63], 0, v[6:7]
	global_store_dwordx4 v[6:7], v[58:61], off
	s_nop 0
	v_cvt_pk_bf16_f32 v58, v136, v137
	v_cvt_pk_bf16_f32 v59, v138, v139
	v_cvt_pk_bf16_f32 v60, v140, v141
	v_cvt_pk_bf16_f32 v61, v142, v143
	v_add_u32_e32 v6, s2, v55
	v_ashrrev_i32_e32 v7, 31, v6
	v_lshlrev_b64 v[6:7], 12, v[6:7]
	v_lshl_add_u64 v[6:7], v[62:63], 0, v[6:7]
	global_store_dwordx4 v[6:7], v[58:61], off
	s_waitcnt lgkmcnt(0)
